# phase header: second kernarg scalar load issued before the first wait (one SMEM round trip less per phase)
# speedup vs baseline: 1.0026x; 1.0001x over previous
; __device__ __forceinline__ float bf2f(bf16_t v) { return __uint_as_float(((unsigned)v) << 16); }
; template <int MODE>
; __device__ __forceinline__ void sample_gemm(const Params& p, int l, const int tid) {
;     const int wid = tid >> 6, lane = tid & 63, r16 = lane & 15, quad = lane >> 4;
;     const bf16_t* A = (const bf16_t*)(p.ws + (MODE == 2 ? WS_H : WS_MERGED)) + (size_t)MP * 2048;
;     const bf16_t* Bt = (const bf16_t*)(p.ws + (MODE == 2 ? WS_WP : WS_WO));
;     for (int sl = blockIdx.x; sl < 128; sl += gridDim.x) {
;         const int n0 = sl * 16;
;         const bf16_t* a0 = A + (size_t)(wid * 32 + r16) * 2048 + quad * 8; const bf16_t* a1 = a0 + 16 * 2048; const bf16_t* bp = Bt + (size_t)(n0 + r16) * 2048 + quad * 8;
;         f32x4 c[2][2];
; #pragma unroll
;         for (int i = 0; i < 2; ++i)
; #pragma unroll
;             for (int j = 0; j < 2; ++j) c[i][j] = (f32x4){0.f, 0.f, 0.f, 0.f};
; #pragma unroll
;         for (int hh = 0; hh < 2; ++hh) {
; #pragma unroll 8
;             for (int k = hh * 1024; k < hh * 1024 + 1024; k += 32) {
;                 const bf16x8 fa0 = *(const bf16x8*)(a0 + k), fa1 = *(const bf16x8*)(a1 + k), fb = *(const bf16x8*)(bp + k);
;                 const int ci = (MODE == 2) ? hh : 0;
;                 c[ci][0] = __builtin_amdgcn_mfma_f32_16x16x32_bf16(fa0, fb, c[ci][0], 0, 0, 0);
;                 c[ci][1] = __builtin_amdgcn_mfma_f32_16x16x32_bf16(fa1, fb, c[ci][1], 0, 0, 0);
;             }
;         }
;         const int col = n0 + r16;
; #pragma unroll
;         for (int i = 0; i < 2; ++i)
; #pragma unroll
;             for (int j = 0; j < 4; ++j) {
;                 const int row = MP + wid * 32 + i * 16 + quad * 4 + j;
;                 if (MODE == 2) {
;                     const float sa = bf2f(((const bf16_t*)(p.ws + WS_MA))[(size_t)row * 2048 + col]), sb = bf2f(((const bf16_t*)(p.ws + WS_MB))[(size_t)row * 2048 + col]);
; __global__ void __launch_bounds__(512, 2) mega(Params p) {
;     ...
;         int z = 0; asm volatile("" : "+s"(z));
;         asm volatile("" : "+s"(pp));
;         Params q;
; #pragma unroll
;         for (int i = 0; i < 22; ++i) q.in[i] = pp->in[i];
;         q.out = pp->out; q.ws = pp->ws; q.ph_lo = 0; q.ph_hi = 0;
;         const int tid = (int)threadIdx.x + z;
;         const int l = ph / NPH, s = ph % NPH;
.LBB0_10:
	v_readlane_b32 s20, v248, 4
	s_mov_b32 s2, s79
	v_readlane_b32 s21, v248, 5
	s_load_dwordx16 s[4:19], s[20:21], 0x0
	v_writelane_b32 v246, s80, 27
	v_add_u32_e32 v188, s2, v204
	s_mov_b32 s1, s79
	v_writelane_b32 v246, s81, 28
	v_writelane_b32 v246, s82, 29
	v_writelane_b32 v246, s83, 30
	s_load_dwordx16 s[76:91], s[20:21], 0x78
	s_waitcnt lgkmcnt(0)
	v_writelane_b32 v246, s4, 31
	v_writelane_b32 v248, s20, 4
	v_writelane_b32 v246, s5, 32
	v_writelane_b32 v246, s6, 33
	v_writelane_b32 v246, s7, 34
	v_writelane_b32 v246, s8, 35
	v_writelane_b32 v246, s9, 36
	v_writelane_b32 v246, s10, 37
	v_writelane_b32 v246, s11, 38
	v_writelane_b32 v246, s12, 39
	v_writelane_b32 v246, s13, 40
	v_writelane_b32 v246, s14, 41
	v_writelane_b32 v246, s15, 42
	v_writelane_b32 v246, s16, 43
	v_writelane_b32 v246, s17, 44
	v_writelane_b32 v246, s18, 45
	v_writelane_b32 v246, s19, 46
	s_load_dwordx2 s[8:9], s[20:21], 0xb8
	v_readlane_b32 s4, v246, 27
	v_readlane_b32 s6, v246, 29
	s_mul_hi_i32 s2, s6, 0x2aaaaaab
	s_lshr_b32 s3, s2, 31
	s_ashr_i32 s2, s2, 1
	s_add_i32 s4, s2, s3
	s_mov_b32 s2, s4
	v_readlane_b32 s5, v246, 28
	v_readlane_b32 s7, v246, 30
	v_writelane_b32 v246, s2, 47
	s_movk_i32 s0, 0x1800
	v_writelane_b32 v248, s21, 5
	v_writelane_b32 v246, s3, 48
	s_mul_i32 s2, s4, 12
	s_sub_i32 s4, s6, s2
	v_writelane_b32 v246, s4, 49
	s_cmp_lt_i32 s4, 5
	s_mov_b64 s[4:5], 0
	v_writelane_b32 v246, s4, 50
	s_mov_b64 s[2:3], -1
	s_nop 0
	v_writelane_b32 v246, s5, 51
	s_waitcnt lgkmcnt(0)
	v_writelane_b32 v246, s8, 52
	s_nop 1
	v_writelane_b32 v246, s9, 53
	s_cbranch_scc1 .LBB0_351
	v_readlane_b32 s4, v246, 49
	s_cmp_gt_i32 s4, 7
	s_mov_b64 s[4:5], 0
	v_writelane_b32 v246, s4, 50
	s_mov_b64 s[16:17], 0
	s_nop 0
	v_writelane_b32 v246, s5, 51
	s_mov_b64 s[4:5], 0
	s_cbranch_scc0 .LBB0_102
	v_readlane_b32 s6, v246, 49
	s_cmp_gt_i32 s6, 8
	s_mov_b64 s[6:7], 0
	s_mov_b64 s[4:5], -1
	s_mov_b64 s[2:3], 0
	v_writelane_b32 v246, s6, 50
	s_nop 1
	v_writelane_b32 v246, s7, 51
	s_cbranch_scc0 .LBB0_102
	v_readlane_b32 s4, v246, 49
	s_cmp_gt_i32 s4, 9
	s_cbranch_scc0 .LBB0_89
	s_cmp_eq_u32 s4, 10
	s_mov_b64 s[4:5], -1
	v_writelane_b32 v246, s4, 50
	s_nop 1
	v_writelane_b32 v246, s5, 51
	s_cbranch_scc0 .LBB0_90
	v_readlane_b32 s4, v248, 8
	v_readlane_b32 s5, v248, 9
	s_andn2_b64 vcc, exec, s[4:5]
	s_waitcnt vmcnt(0)
	v_and_b32_e32 v44, 15, v188
	s_cbranch_vccnz .LBB0_22
	v_ashrrev_i32_e32 v0, 1, v188
	v_bfe_u32 v4, v188, 4, 2
	v_and_b32_e32 v5, 0xffffffe0, v0
	v_lshl_or_b32 v6, v4, 2, v5
	v_add_u32_e32 v0, 0x8000, v6
	v_ashrrev_i32_e32 v1, 31, v0
	v_lshlrev_b64 v[18:19], 11, v[0:1]
	v_add_u32_e32 v0, 0x8001, v6
	v_ashrrev_i32_e32 v1, 31, v0
	v_lshlrev_b64 v[20:21], 11, v[0:1]
	v_add_u32_e32 v0, 0x8002, v6
	v_ashrrev_i32_e32 v1, 31, v0
	v_readlane_b32 s4, v248, 4
	v_lshlrev_b64 v[22:23], 11, v[0:1]
	v_add_u32_e32 v0, 0x8003, v6
	v_readlane_b32 s5, v248, 5
	v_ashrrev_i32_e32 v1, 31, v0
	s_load_dwordx2 s[10:11], s[4:5], 0xb8
	v_lshlrev_b64 v[24:25], 11, v[0:1]
	v_add_u32_e32 v0, 0x8011, v6
	v_ashrrev_i32_e32 v1, 31, v0
	v_lshlrev_b64 v[26:27], 11, v[0:1]
	v_add_u32_e32 v0, 0x8012, v6
	v_ashrrev_i32_e32 v1, 31, v0
	v_lshlrev_b64 v[28:29], 11, v[0:1]
	v_add_u32_e32 v0, 0x8013, v6
	s_waitcnt lgkmcnt(0)
	s_add_u32 s4, s10, 0x2c600000
	v_ashrrev_i32_e32 v1, 31, v0
	s_addc_u32 s5, s11, 0
	v_lshlrev_b64 v[30:31], 11, v[0:1]
	v_or_b32_e32 v0, v5, v44
	s_add_u32 s6, s10, 0x34700000
	v_ashrrev_i32_e32 v1, 31, v0
	s_addc_u32 s7, s11, 0
	v_add_u32_e32 v2, 0x8010, v6
	v_lshlrev_b64 v[0:1], 12, v[0:1]
	s_add_u32 s8, s10, 0xc200000
	v_ashrrev_i32_e32 v3, 31, v2
	v_lshl_add_u64 v[32:33], s[10:11], 0, v[0:1]
	v_readlane_b32 s10, v247, 29
	s_addc_u32 s9, s11, 0
	v_lshlrev_b64 v[16:17], 11, v[2:3]
	v_lshlrev_b32_e32 v136, 4, v4
	v_add_u32_e32 v34, s10, v44
	v_readlane_b32 s10, v247, 56
